# static priority raise for waves 4-7 during the indexer/top-k task loop
# baseline (speedup 1.0000x reference)
; DI float bf2f(bf16_t b) { return __uint_as_float(((unsigned)b) << 16); }
; DI int pi_row(int r) { return (r & 3) | (((r >> 3) & 1) << 2) | (((r >> 2) & 1) << 3) | (r & 16); }
; DI void a1_task(unsigned char* shm, const bf16_t* prm, const bf16_t* prt, unsigned* mask, int b, int qt, const int tid) {
;     const int wid = __builtin_amdgcn_readfirstlane(tid >> 6), lane = tid & 63, r = lane & 31, h = lane >> 5;
;     const int t0 = qt * 32, tok0 = b * SEQ;
;     unsigned* cnt = (unsigned*)(shm + 33280);
;     { u32x4 t[4];
; #pragma unroll
;       for (int p = 0; p < 4; ++p) { const int c = tid + p * 512, row = c >> 6, ch = c & 63; t[p] = *(const u32x4*)(prm + (size_t)(tok0 + t0 + row) * RM_LD + C_IQ + ch * 8); }
; #pragma unroll
;       for (int p = 0; p < 4; ++p) { const int c = tid + p * 512, row = c >> 6, ch = c & 63; *(u32x4*)(shm + row * 1040 + ch * 16) = t[p]; } }
;     cnt[tid] = 0u; cnt[tid + 512] = 0u;
;     float* wqs = (float*)(shm + 33280 + 4096);
;     if (tid < 256) wqs[tid] = bf2f(prt[(size_t)(R_IW + (tid >> 5)) * MTOK + tok0 + t0 + (tid & 31)]);
;     __syncthreads();
;     unsigned key[8][16];
;     const bf16_t* kp = prm + (size_t)(tok0 + pi_row(r)) * RM_LD + C_IK + 8 * h;
; DI void phase_a1(const Args& a, unsigned char* shm, const int tid) {
;     ...
;     for (int k = 0;; ++k) { int b, qt; if (!task_map(k, b, qt)) break; a1_task(shm, prm, prt, mask, b, qt, tid); }
.LBB0_367:
	s_andn2_b64 vcc, exec, s[0:1]
	s_mov_b64 s[8:9], 0
	s_cbranch_vccnz .LBB0_534
	v_readlane_b32 s0, v255, 28
	s_cmp_gt_i32 s0, 0
	s_mov_b64 s[0:1], -1
	s_cbranch_scc0 .LBB0_532
	v_add_u32_e32 v0, 0x200, v210
	v_ashrrev_i32_e32 v113, 6, v0
	v_add_u32_e32 v0, 0x400, v210
	v_ashrrev_i32_e32 v114, 6, v0
	v_add_u32_e32 v0, 0x600, v210
	v_ashrrev_i32_e32 v112, 6, v210
	v_ashrrev_i32_e32 v115, 6, v0
	s_movk_i32 s0, 0x410
	v_mul_lo_u32 v5, v112, s0
	v_mul_lo_u32 v6, v113, s0
	v_mul_lo_u32 v7, v114, s0
	v_mul_lo_u32 v8, v115, s0
	s_movk_i32 s0, 0x100
	v_cmp_gt_i32_e64 s[0:1], s0, v210
	v_ashrrev_i32_e32 v2, 5, v210
	v_ashrrev_i32_e32 v3, 31, v2
	v_writelane_b32 v255, s0, 29
	v_lshlrev_b64 v[2:3], 17, v[2:3]
	v_lshrrev_b32_e32 v110, 1, v210
	v_writelane_b32 v255, s1, 30
	v_readlane_b32 s0, v251, 21
	v_readlane_b32 s1, v251, 22
	v_and_b32_e32 v9, 19, v210
	v_and_b32_e32 v11, 64, v233
	v_lshl_add_u64 v[2:3], s[0:1], 0, v[2:3]
	s_mov_b64 s[0:1], 0x5800000
	v_lshl_add_u64 v[102:103], v[2:3], 0, s[0:1]
	v_lshlrev_b32_e32 v3, 1, v210
	v_and_b32_e32 v2, 4, v110
	v_and_b32_e32 v3, 8, v3
	v_or3_b32 v117, v2, v9, v3
	v_xor_b32_e32 v3, 32, v233
	v_add_u32_e32 v119, 64, v11
	s_mov_b32 s0, 0
	v_cmp_lt_i32_e32 vcc, v3, v119
	v_lshlrev_b32_e32 v101, 4, v210
	v_bfe_u32 v99, v210, 5, 1
	v_writelane_b32 v255, s0, 31
	v_cndmask_b32_e32 v3, v233, v3, vcc
	v_readlane_b32 s0, v254, 55
	v_and_b32_e32 v100, 31, v210
	v_and_b32_e32 v0, 0x3f0, v101
	v_lshlrev_b32_e32 v2, 4, v99
	v_lshlrev_b32_e32 v148, 2, v3
	v_readlane_b32 s1, v254, 56
	v_mov_b32_e32 v3, v1
	v_mul_u32_u24_e32 v9, 0x410, v100
	v_mul_i32_i24_e32 v10, 0xfffffbf4, v100
	v_cmp_eq_u32_e64 s[58:59], 0, v99
	v_lshl_add_u64 v[104:105], s[0:1], 0, v[0:1]
	v_lshl_add_u64 v[106:107], s[0:1], 0, v[2:3]
	v_readlane_b32 s0, v254, 34
	v_add_u32_e32 v4, 0, v0
	v_lshlrev_b32_e32 v98, 3, v99
	v_add3_u32 v135, v9, v10, s0
	v_readlane_b32 s0, v254, 35
	v_writelane_b32 v255, s58, 33
	v_lshlrev_b32_e32 v111, 3, v210
	v_lshl_add_u32 v116, v210, 2, 0
	v_add3_u32 v118, 0, v9, v2
	v_or_b32_e32 v120, 1, v98
	v_or_b32_e32 v121, 2, v98
	v_or_b32_e32 v122, 3, v98
	v_or_b32_e32 v123, 4, v98
	v_or_b32_e32 v124, 5, v98
	v_or_b32_e32 v125, 6, v98
	v_or_b32_e32 v126, 7, v98
	v_or_b32_e32 v127, 16, v98
	v_or_b32_e32 v128, 17, v98
	v_or_b32_e32 v129, 18, v98
	v_or_b32_e32 v130, 19, v98
	v_or_b32_e32 v131, 20, v98
	v_or_b32_e32 v132, 21, v98
	v_or_b32_e32 v133, 22, v98
	v_or_b32_e32 v134, 23, v98
	v_lshl_add_u32 v136, v100, 2, s0
	v_add_u32_e32 v137, v4, v5
	v_add_u32_e32 v138, v4, v6
	v_add_u32_e32 v139, v4, v7
	v_add_u32_e32 v140, v4, v8
	v_writelane_b32 v255, s59, 34
	v_readfirstlane_b32 s6, v210
	s_nop 3
	s_lshr_b32 s6, s6, 6
	s_cmp_ge_u32 s6, 4
	s_cbranch_scc0 .Lprio_a1
	s_setprio 1
.Lprio_a1:
	s_branch .LBB0_373
.LBB0_370:
	s_or_b64 exec, exec, s[0:1]

; DI float bf_lo(unsigned w) { return __uint_as_float(w << 16); }
; DI float bf_hi(unsigned w) { return __uint_as_float(w & 0xFFFF0000u); }
; DI void phase_a1(const Args& a, unsigned char* shm, const int tid) {
;     ...
;     for (int j = 2048 + blockIdx.x; j < 2048 + 192; j += gridDim.x) {
;         {
;             const int id = (j - 2048) * 8 + (tid >> 6), lane = tid & 63;
;             const int b = id / 48, hd = (id >> 3) % 6, n = id & 7;
;             const int c8 = lane & 7, rr = lane >> 3;
;             const bf16_t* p = prm + (size_t)(b * SEQ + n * 256 + rr) * RM_LD + C_CK + hd * 64 + 8 * c8;
;             float acc[8];
; #pragma unroll
;             for (int e = 0; e < 8; ++e) acc[e] = 0.f;
; #pragma unroll 1
;             for (int t0 = 0; t0 < 256; t0 += 64) {
;                 u32x4 v[8];
; #pragma unroll
;                 for (int q = 0; q < 8; ++q) v[q] = *(const u32x4*)(p + (size_t)(t0 + 8 * q) * RM_LD);
; #pragma unroll
;                 for (int q = 0; q < 8; ++q) { acc[0] += bf_lo(v[q].x); acc[1] += bf_hi(v[q].x); acc[2] += bf_lo(v[q].y); acc[3] += bf_hi(v[q].y);
;                                               acc[4] += bf_lo(v[q].z); acc[5] += bf_hi(v[q].z); acc[6] += bf_lo(v[q].w); acc[7] += bf_hi(v[q].w); }
;             }
; #pragma unroll
;             for (int e = 0; e < 8; ++e) { acc[e] += __shfl_xor(acc[e], 8); acc[e] += __shfl_xor(acc[e], 16); acc[e] += __shfl_xor(acc[e], 32); }
.LBB0_511:
	s_setprio 0
	v_readlane_b32 s0, v251, 30
	v_readlane_b32 s1, v251, 31
	s_andn2_b64 vcc, exec, s[0:1]
	v_bfe_u32 v9, v210, 3, 3
	s_mov_b32 s6, 0x2aaaaaab
	s_cbranch_vccnz .LBB0_518
	v_xor_b32_e32 v0, 8, v233
	v_cmp_lt_i32_e32 vcc, v0, v119
	v_and_b32_e32 v2, 56, v111
	v_readlane_b32 s0, v251, 25
	v_cndmask_b32_e32 v0, v233, v0, vcc
	v_lshlrev_b32_e32 v24, 2, v0
	v_xor_b32_e32 v0, 16, v233
	v_cmp_lt_i32_e32 vcc, v0, v119
	v_bfe_u32 v23, v210, 6, 3
	v_readlane_b32 s1, v251, 26
	v_cndmask_b32_e32 v0, v233, v0, vcc
	v_lshlrev_b32_e32 v25, 2, v0
	v_lshlrev_b32_e32 v0, 2, v2
	v_add_u32_e32 v22, 0xffffc000, v112
	v_cmp_eq_u32_e64 s[38:39], 0, v9
	v_lshl_add_u64 v[6:7], s[0:1], 0, v[0:1]
	v_lshl_or_b32 v26, v23, 8, v9
	v_lshlrev_b32_e32 v0, 1, v2
	v_readlane_b32 s2, v251, 29
	s_branch .LBB0_514
